# S5 local pass: U-tile LDS staging deferred behind the direction-0 fragment loads
# speedup vs baseline: 1.0049x; 1.0049x over previous
.LBB0_599:
	s_and_b32 s0, s8, 8
	v_mov_b64_e32 v[4:5], s[4:5]
	s_add_i32 s0, s0, s7
	v_mad_i64_i32 v[2:3], s[4:5], v2, s94, v[4:5]
	s_lshl_b32 s4, s0, 4
	s_ashr_i32 s5, s4, 31
	v_lshl_add_u64 v[2:3], s[4:5], 1, v[2:3]
	s_mov_b64 s[4:5], 0xe001000
	v_add_co_u32_e32 v6, vcc, 0xe001000, v2
	v_lshl_add_u64 v[4:5], v[2:3], 0, s[4:5]
	s_nop 0
	v_addc_co_u32_e32 v7, vcc, 0, v3, vcc
	global_load_dwordx4 v[222:225], v[4:5], off offset:16
	s_nop 0
	global_load_dwordx4 v[226:229], v[6:7], off
	s_lshr_b32 s1, s11, 6
	s_mulk_i32 s1, 0x3e00
	s_add_i32 s1, s1, 0
	v_mad_u32_u24 v0, v0, 48, s1
	v_mov_b32_e32 v230, v0
	v_mov_b32_e32 v37, v204
	v_mov_b32_e32 v10, s59
	s_add_i32 s4, s0, s21
	s_ashr_i32 s5, s4, 31
	s_lshl_b64 s[22:23], s[4:5], 13
	v_mov_b32_e32 v11, v1
	s_mov_b32 s11, 0x200000
	v_mov_b32_e32 v36, 0
	v_mov_b32_e32 v38, 0
	v_mov_b32_e32 v39, 0
	v_mov_b32_e32 v40, 0
	v_mov_b32_e32 v41, 0
	s_waitcnt lgkmcnt(0)
	s_waitcnt lgkmcnt(0)
	ds_read_b64 v[2:3], v10
	v_readfirstlane_b32 s1, v37
	v_and_b32_e32 v136, 63, v37
	s_lshr_b32 s1, s1, 6
	v_lshl_or_b32 v4, s4, 6, v136
	s_mulk_i32 s1, 0x3e00
	v_ashrrev_i32_e32 v5, 31, v4
	s_add_i32 s1, s1, 0
	s_waitcnt lgkmcnt(0)
	v_readfirstlane_b32 s5, v3
	v_readfirstlane_b32 s4, v2
	v_and_b32_e32 v42, 15, v37
	v_and_b32_e32 v0, 48, v37
	v_lshl_add_u64 v[2:3], v[4:5], 4, s[4:5]
	s_add_u32 s4, s4, s22
	s_addc_u32 s5, s5, s23
	v_lshlrev_b32_e32 v10, 6, v42
	v_lshl_add_u64 v[4:5], s[4:5], 0, v[0:1]
	v_add_co_u32_e32 v2, vcc, s11, v2
	v_lshl_add_u64 v[6:7], v[4:5], 0, v[10:11]
	s_mov_b64 s[4:5], 0x240000
	v_addc_co_u32_e32 v3, vcc, 0, v3, vcc
	v_lshl_add_u64 v[8:9], v[6:7], 0, s[4:5]
	s_mov_b32 s4, 0x240000
	v_add_co_u32_e32 v10, vcc, s4, v6
	global_load_dwordx2 v[2:3], v[2:3], off
	s_nop 0
	global_load_dwordx4 v[28:31], v[8:9], off offset:1024
	global_load_dwordx4 v[20:23], v[8:9], off offset:2048
	global_load_dwordx4 v[12:15], v[8:9], off offset:3072
	s_mov_b64 s[36:37], vcc
	s_waitcnt lgkmcnt(0)
	v_add_co_u32_e32 v4, vcc, 0x241000, v6
	v_addc_co_u32_e64 v11, s[36:37], 0, v7, s[36:37]
	s_nop 0
	v_addc_co_u32_e32 v5, vcc, 0, v7, vcc
	global_load_dwordx4 v[32:35], v[10:11], off
	global_load_dwordx4 v[24:27], v[4:5], off
	global_load_dwordx4 v[16:19], v[4:5], off offset:1024
	s_nop 0
	global_load_dwordx4 v[8:11], v[4:5], off offset:2048
	s_nop 0
	global_load_dwordx4 v[4:7], v[4:5], off offset:3072
	v_add_u32_e32 v0, s1, v0
	v_cmp_gt_u32_e32 vcc, 32, v136
	v_mad_u32_u24 v158, v42, 48, v0
	s_waitcnt vmcnt(9)
	ds_write_b128 v230, v[222:225] offset:16
	ds_write_b128 v230, v[226:229]
	s_and_saveexec_b64 s[4:5], vcc
	ds_read_b128 v[38:41], v158
	s_or_b64 exec, exec, s[4:5]
	s_waitcnt vmcnt(0) lgkmcnt(0)
	v_mfma_f32_16x16x32_bf16 v[44:47], v[38:41], v[32:35], 0
	v_bfe_u32 v0, v37, 4, 2
	v_lshlrev_b32_e32 v37, 2, v42
	v_mul_u32_u24_e32 v0, 0x840, v0
	v_mfma_f32_16x16x32_bf16 v[48:51], v[38:41], v[28:31], 0
	v_add3_u32 v37, s1, v37, v0
	v_add_u32_e32 v0, 0xc00, v37
	v_add_u32_e32 v137, 0x1000, v37
	v_mfma_f32_16x16x32_bf16 v[52:55], v[38:41], v[20:23], 0
	v_lshl_add_u32 v138, v136, 2, s1
	s_nop 2
	ds_write2_b32 v0, v44, v48 offset1:16
	ds_write2_b32 v0, v45, v49 offset0:132 offset1:148
	v_mfma_f32_16x16x32_bf16 v[56:59], v[38:41], v[12:15], 0
	ds_write2_b32 v137, v46, v50 offset0:8 offset1:24
	ds_write2_b32 v137, v47, v51 offset0:140 offset1:156
	s_nop 5
	ds_write2_b32 v0, v52, v56 offset0:32 offset1:48
	ds_write2_b32 v0, v53, v57 offset0:164 offset1:180
	v_mfma_f32_16x16x32_bf16 v[42:45], v[38:41], v[24:27], 0
	v_add_u32_e32 v139, 16, v138
	v_add_u32_e32 v140, 32, v138
	v_add_u32_e32 v141, 48, v138
	v_mfma_f32_16x16x32_bf16 v[46:49], v[38:41], v[16:19], 0
	ds_write2_b32 v137, v54, v58 offset0:40 offset1:56
	ds_write2_b32 v137, v55, v59 offset0:172 offset1:188
	s_nop 5
	ds_write2_b32 v0, v42, v46 offset0:64 offset1:80
	ds_write2_b32 v0, v43, v47 offset0:196 offset1:212
	ds_write2_b32 v137, v44, v48 offset0:72 offset1:88
	ds_write2_b32 v137, v45, v49 offset0:204 offset1:220
	v_mfma_f32_16x16x32_bf16 v[50:53], v[38:41], v[8:11], 0
	v_add_u32_e32 v146, 64, v138
	v_add_u32_e32 v147, 0x50, v138
	v_add_u32_e32 v148, 0x60, v138
	v_mfma_f32_16x16x32_bf16 v[38:41], v[38:41], v[4:7], 0
	s_nop 7
	ds_write2_b32 v0, v50, v38 offset0:96 offset1:112
	ds_write2_b32 v0, v51, v39 offset0:228 offset1:244
	ds_write2_b32 v137, v52, v40 offset0:104 offset1:120
	ds_write2_b32 v137, v53, v41 offset0:236 offset1:252
	s_waitcnt lgkmcnt(0)
	v_add_u32_e32 v149, 0x70, v138
	v_add_u32_e32 v150, 0x80, v138
	v_add_u32_e32 v151, 0x90, v138
	v_add_u32_e32 v152, 0xa0, v138
	v_add_u32_e32 v153, 0xb0, v138
	v_add_u32_e32 v154, 0xc0, v138
	v_add_u32_e32 v155, 0xd0, v138
	v_add_u32_e32 v156, 0xe0, v138
	v_add_u32_e32 v157, 0xf0, v138
	ds_read2st64_b32 v[134:135], v138 offset0:12 offset1:13
	ds_read2st64_b32 v[132:133], v139 offset0:14 offset1:15
	ds_read2st64_b32 v[130:131], v140 offset0:16 offset1:17
	ds_read2st64_b32 v[128:129], v141 offset0:18 offset1:19
	ds_read2st64_b32 v[124:125], v146 offset0:20 offset1:21
	ds_read2st64_b32 v[120:121], v147 offset0:22 offset1:23
	ds_read2st64_b32 v[116:117], v148 offset0:24 offset1:25
	ds_read2st64_b32 v[112:113], v149 offset0:26 offset1:27
	ds_read2st64_b32 v[108:109], v150 offset0:28 offset1:29
	ds_read2st64_b32 v[102:103], v151 offset0:30 offset1:31
	ds_read2st64_b32 v[98:99], v152 offset0:32 offset1:33
	ds_read2st64_b32 v[94:95], v153 offset0:34 offset1:35
	ds_read2st64_b32 v[88:89], v154 offset0:36 offset1:37
	ds_read2st64_b32 v[82:83], v155 offset0:38 offset1:39
	ds_read2st64_b32 v[76:77], v156 offset0:40 offset1:41
	ds_read2st64_b32 v[70:71], v157 offset0:42 offset1:43
	s_waitcnt lgkmcnt(0)
	v_mov_b32_e32 v37, 0
	v_mov_b32_e32 v38, 0
	v_mov_b32_e32 v39, 0
	s_and_saveexec_b64 s[4:5], vcc
	ds_read_b128 v[36:39], v158 offset:768
	s_or_b64 exec, exec, s[4:5]
	s_waitcnt lgkmcnt(0)
	v_mfma_f32_16x16x32_bf16 v[40:43], v[36:39], v[32:35], 0
	v_mfma_f32_16x16x32_bf16 v[44:47], v[36:39], v[28:31], 0
	s_nop 7
	ds_write2_b32 v0, v40, v44 offset1:16
	ds_write2_b32 v0, v41, v45 offset0:132 offset1:148
	ds_write2_b32 v137, v42, v46 offset0:8 offset1:24
	v_mfma_f32_16x16x32_bf16 v[48:51], v[36:39], v[20:23], 0
	v_mfma_f32_16x16x32_bf16 v[52:55], v[36:39], v[12:15], 0
	ds_write2_b32 v137, v43, v47 offset0:140 offset1:156
	s_nop 6
	ds_write2_b32 v0, v48, v52 offset0:32 offset1:48
	ds_write2_b32 v0, v49, v53 offset0:164 offset1:180
	v_mfma_f32_16x16x32_bf16 v[56:59], v[36:39], v[24:27], 0
	v_mfma_f32_16x16x32_bf16 v[40:43], v[36:39], v[16:19], 0
	ds_write2_b32 v137, v50, v54 offset0:40 offset1:56
	ds_write2_b32 v137, v51, v55 offset0:172 offset1:188
	s_nop 5
	ds_write2_b32 v0, v56, v40 offset0:64 offset1:80
	ds_write2_b32 v0, v57, v41 offset0:196 offset1:212
	ds_write2_b32 v137, v58, v42 offset0:72 offset1:88
	ds_write2_b32 v137, v59, v43 offset0:204 offset1:220
	v_mfma_f32_16x16x32_bf16 v[44:47], v[36:39], v[8:11], 0
	v_mov_b32_e32 v40, 0
	v_mov_b32_e32 v41, 0
	v_mfma_f32_16x16x32_bf16 v[36:39], v[36:39], v[4:7], 0
	s_nop 7
	ds_write2_b32 v0, v44, v36 offset0:96 offset1:112
	ds_write2_b32 v0, v45, v37 offset0:228 offset1:244
	ds_write2_b32 v137, v46, v38 offset0:104 offset1:120
	ds_write2_b32 v137, v47, v39 offset0:236 offset1:252
	s_waitcnt lgkmcnt(0)
	ds_read2st64_b32 v[126:127], v138 offset0:12 offset1:13
	ds_read2st64_b32 v[122:123], v139 offset0:14 offset1:15
	ds_read2st64_b32 v[118:119], v140 offset0:16 offset1:17
	ds_read2st64_b32 v[114:115], v141 offset0:18 offset1:19
	ds_read2st64_b32 v[110:111], v146 offset0:20 offset1:21
	ds_read2st64_b32 v[104:105], v147 offset0:22 offset1:23
	ds_read2st64_b32 v[96:97], v148 offset0:24 offset1:25
	ds_read2st64_b32 v[90:91], v149 offset0:26 offset1:27
	ds_read2st64_b32 v[84:85], v150 offset0:28 offset1:29
	ds_read2st64_b32 v[78:79], v151 offset0:30 offset1:31
	ds_read2st64_b32 v[72:73], v152 offset0:32 offset1:33
	ds_read2st64_b32 v[66:67], v153 offset0:34 offset1:35
	ds_read2st64_b32 v[62:63], v154 offset0:36 offset1:37
	ds_read2st64_b32 v[58:59], v155 offset0:38 offset1:39
	ds_read2st64_b32 v[54:55], v156 offset0:40 offset1:41
	ds_read2st64_b32 v[50:51], v157 offset0:42 offset1:43
	s_waitcnt lgkmcnt(0)
	v_mov_b32_e32 v36, 0
	v_mov_b32_e32 v38, 0
	v_mov_b32_e32 v39, 0
	s_and_saveexec_b64 s[4:5], vcc
	ds_read_b128 v[38:41], v158 offset:1536
	s_or_b64 exec, exec, s[4:5]
	s_waitcnt lgkmcnt(0)
	v_mfma_f32_16x16x32_bf16 v[42:45], v[38:41], v[32:35], 0
	v_mov_b32_e32 v37, 0
	v_mfma_f32_16x16x32_bf16 v[46:49], v[38:41], v[28:31], 0
	s_nop 7
	ds_write2_b32 v0, v42, v46 offset1:16
	ds_write2_b32 v0, v43, v47 offset0:132 offset1:148
	ds_write2_b32 v137, v44, v48 offset0:8 offset1:24
	v_mfma_f32_16x16x32_bf16 v[160:163], v[38:41], v[20:23], 0
	v_mfma_f32_16x16x32_bf16 v[164:167], v[38:41], v[12:15], 0
	ds_write2_b32 v137, v45, v49 offset0:140 offset1:156
	s_nop 6
	ds_write2_b32 v0, v160, v164 offset0:32 offset1:48
	ds_write2_b32 v0, v161, v165 offset0:164 offset1:180
	v_mfma_f32_16x16x32_bf16 v[168:171], v[38:41], v[24:27], 0
	v_mfma_f32_16x16x32_bf16 v[42:45], v[38:41], v[16:19], 0
	ds_write2_b32 v137, v162, v166 offset0:40 offset1:56
	ds_write2_b32 v137, v163, v167 offset0:172 offset1:188
	s_nop 5
	ds_write2_b32 v0, v168, v42 offset0:64 offset1:80
	ds_write2_b32 v0, v169, v43 offset0:196 offset1:212
	ds_write2_b32 v137, v170, v44 offset0:72 offset1:88
	ds_write2_b32 v137, v171, v45 offset0:204 offset1:220
	v_mfma_f32_16x16x32_bf16 v[46:49], v[38:41], v[8:11], 0
	v_mfma_f32_16x16x32_bf16 v[38:41], v[38:41], v[4:7], 0
	s_nop 7
	ds_write2_b32 v0, v46, v38 offset0:96 offset1:112
	ds_write2_b32 v0, v47, v39 offset0:228 offset1:244
	ds_write2_b32 v137, v48, v40 offset0:104 offset1:120
	ds_write2_b32 v137, v49, v41 offset0:236 offset1:252
	s_waitcnt lgkmcnt(0)
	ds_read2st64_b32 v[106:107], v138 offset0:12 offset1:13
	ds_read2st64_b32 v[100:101], v139 offset0:14 offset1:15
	ds_read2st64_b32 v[92:93], v140 offset0:16 offset1:17
	ds_read2st64_b32 v[86:87], v141 offset0:18 offset1:19
	ds_read2st64_b32 v[80:81], v146 offset0:20 offset1:21
	ds_read2st64_b32 v[74:75], v147 offset0:22 offset1:23
	ds_read2st64_b32 v[68:69], v148 offset0:24 offset1:25
	ds_read2st64_b32 v[64:65], v149 offset0:26 offset1:27
	ds_read2st64_b32 v[60:61], v150 offset0:28 offset1:29
	ds_read2st64_b32 v[56:57], v151 offset0:30 offset1:31
	ds_read2st64_b32 v[52:53], v152 offset0:32 offset1:33
	ds_read2st64_b32 v[48:49], v153 offset0:34 offset1:35
	ds_read2st64_b32 v[46:47], v154 offset0:36 offset1:37
	ds_read2st64_b32 v[44:45], v155 offset0:38 offset1:39
	ds_read2st64_b32 v[42:43], v156 offset0:40 offset1:41
	ds_read2st64_b32 v[40:41], v157 offset0:42 offset1:43
	s_waitcnt lgkmcnt(0)
	v_mov_b32_e32 v38, 0
	v_mov_b32_e32 v39, 0
	s_and_saveexec_b64 s[4:5], vcc
	ds_read_b128 v[36:39], v158 offset:2304
	s_or_b64 exec, exec, s[4:5]
	v_mul_f32_e32 v158, 0, v3
	v_fma_f32 v159, 0, v2, v158
	v_add_f32_e32 v135, v159, v135
	v_fma_f32 v158, v2, 0, -v158
	v_mul_f32_e32 v159, v2, v135
	v_add_f32_e32 v134, v158, v134
	v_mul_f32_e32 v135, v3, v135
	v_fmac_f32_e32 v159, v3, v134
	v_fma_f32 v134, v2, v134, -v135
	v_add_f32_e32 v132, v132, v134
	v_add_f32_e32 v133, v133, v159
	v_fma_f32 v134, v3, v132, v131
	v_fma_f32 v130, v2, v132, v130
	v_fma_f32 v130, -v3, v133, v130
	v_fma_f32 v131, v2, v133, v134
	v_fma_f32 v132, v3, v130, v129
	v_fma_f32 v128, v2, v130, v128
	v_fma_f32 v128, -v3, v131, v128
	v_fma_f32 v129, v2, v131, v132
	v_fma_f32 v130, v3, v128, v125
	v_fma_f32 v124, v2, v128, v124
	v_fma_f32 v124, -v3, v129, v124
	v_fma_f32 v125, v2, v129, v130
	v_fma_f32 v128, v3, v124, v121
	v_fma_f32 v120, v2, v124, v120
	v_fma_f32 v120, -v3, v125, v120
	v_fma_f32 v121, v2, v125, v128
	v_fma_f32 v124, v3, v120, v117
	v_fma_f32 v116, v2, v120, v116
	v_fma_f32 v116, -v3, v121, v116
	v_fma_f32 v117, v2, v121, v124
	v_fma_f32 v120, v3, v116, v113
	v_fma_f32 v112, v2, v116, v112
	v_fma_f32 v112, -v3, v117, v112
	v_fma_f32 v113, v2, v117, v120
	v_fma_f32 v116, v3, v112, v109
	v_fma_f32 v108, v2, v112, v108
	v_fma_f32 v108, -v3, v113, v108
	v_fma_f32 v109, v2, v113, v116
	v_fma_f32 v112, v3, v108, v103
	v_fma_f32 v102, v2, v108, v102
	v_fma_f32 v102, -v3, v109, v102
	v_fma_f32 v103, v2, v109, v112
	v_fma_f32 v108, v3, v102, v99
	v_fma_f32 v98, v2, v102, v98
	v_fma_f32 v98, -v3, v103, v98
	v_fma_f32 v99, v2, v103, v108
	v_fma_f32 v102, v3, v98, v95
	v_fma_f32 v94, v2, v98, v94
	v_fma_f32 v94, -v3, v99, v94
	v_fma_f32 v95, v2, v99, v102
	v_fma_f32 v98, v3, v94, v89
	v_fma_f32 v88, v2, v94, v88
	v_fma_f32 v88, -v3, v95, v88
	v_fma_f32 v89, v2, v95, v98
	v_fma_f32 v94, v3, v88, v83
	v_fma_f32 v82, v2, v88, v82
	v_fma_f32 v82, -v3, v89, v82
	v_fma_f32 v83, v2, v89, v94
	v_fma_f32 v88, v3, v82, v77
	v_fma_f32 v76, v2, v82, v76
	v_fma_f32 v76, -v3, v83, v76
	v_fma_f32 v77, v2, v83, v88
	v_fma_f32 v82, v3, v76, v71
	v_fma_f32 v70, v2, v76, v70
	v_fma_f32 v70, -v3, v77, v70
	v_fma_f32 v71, v2, v77, v82
	v_mul_f32_e32 v76, v3, v70
	v_fmac_f32_e32 v76, v2, v71
	v_mul_f32_e32 v71, v3, v71
	v_add_f32_e32 v76, v76, v127
	v_fma_f32 v70, v2, v70, -v71
	v_mul_f32_e32 v77, v2, v76
	v_add_f32_e32 v70, v70, v126
	v_mul_f32_e32 v76, v3, v76
	v_fmac_f32_e32 v77, v3, v70
	v_fma_f32 v70, v2, v70, -v76
	v_add_f32_e32 v70, v122, v70
	v_add_f32_e32 v71, v123, v77
	v_fma_f32 v76, v3, v70, v119
	v_fma_f32 v70, v2, v70, v118
	v_fma_f32 v70, -v3, v71, v70
	v_fma_f32 v76, v2, v71, v76
	v_fma_f32 v71, v3, v70, v115
	v_fma_f32 v70, v2, v70, v114
	v_fma_f32 v70, -v3, v76, v70
	v_fma_f32 v71, v2, v76, v71
	v_fma_f32 v76, v3, v70, v111
	v_fma_f32 v70, v2, v70, v110
	v_fma_f32 v70, -v3, v71, v70
	v_fma_f32 v76, v2, v71, v76
	v_fma_f32 v71, v3, v70, v105
	v_fma_f32 v70, v2, v70, v104
	v_fma_f32 v70, -v3, v76, v70
	v_fma_f32 v71, v2, v76, v71
	v_fma_f32 v76, v3, v70, v97
	v_fma_f32 v70, v2, v70, v96
	v_fma_f32 v70, -v3, v71, v70
	v_fma_f32 v76, v2, v71, v76
	v_fma_f32 v71, v3, v70, v91
	v_fma_f32 v70, v2, v70, v90
	v_fma_f32 v70, -v3, v76, v70
	v_fma_f32 v71, v2, v76, v71
	v_fma_f32 v76, v3, v70, v85
	v_fma_f32 v70, v2, v70, v84
	v_fma_f32 v70, -v3, v71, v70
	v_fma_f32 v76, v2, v71, v76
	v_fma_f32 v71, v3, v70, v79
	v_fma_f32 v70, v2, v70, v78
	v_fma_f32 v70, -v3, v76, v70
	v_fma_f32 v71, v2, v76, v71
	v_fma_f32 v76, v3, v70, v73
	v_fma_f32 v70, v2, v70, v72
	v_fma_f32 v70, -v3, v71, v70
	v_fma_f32 v73, v2, v71, v76
	v_fma_f32 v71, v3, v70, v67
	v_fma_f32 v66, v2, v70, v66
	v_fma_f32 v66, -v3, v73, v66
	v_fma_f32 v67, v2, v73, v71
	v_fma_f32 v70, v3, v66, v63
	v_fma_f32 v62, v2, v66, v62
	v_fma_f32 v62, -v3, v67, v62
	v_fma_f32 v63, v2, v67, v70
	v_fma_f32 v66, v3, v62, v59
	v_fma_f32 v58, v2, v62, v58
	v_fma_f32 v58, -v3, v63, v58
	v_fma_f32 v59, v2, v63, v66
	v_fma_f32 v62, v3, v58, v55
	v_fma_f32 v54, v2, v58, v54
	v_fma_f32 v54, -v3, v59, v54
	v_fma_f32 v55, v2, v59, v62
	v_fma_f32 v58, v3, v54, v51
	v_fma_f32 v50, v2, v54, v50
	v_fma_f32 v50, -v3, v55, v50
	v_fma_f32 v51, v2, v55, v58
	v_mul_f32_e32 v54, v3, v50
	v_fmac_f32_e32 v54, v2, v51
	v_mul_f32_e32 v51, v3, v51
	s_waitcnt lgkmcnt(14)
	v_add_f32_e32 v54, v54, v107
	v_fma_f32 v50, v2, v50, -v51
	v_mul_f32_e32 v55, v2, v54
	v_add_f32_e32 v50, v50, v106
	v_mul_f32_e32 v54, v3, v54
	v_fmac_f32_e32 v55, v3, v50
	v_fma_f32 v50, v2, v50, -v54
	v_add_f32_e32 v50, v100, v50
	v_add_f32_e32 v51, v101, v55
	s_waitcnt lgkmcnt(13)
	v_fma_f32 v54, v3, v50, v93
	v_fma_f32 v50, v2, v50, v92
	v_fma_f32 v50, -v3, v51, v50
	v_fma_f32 v54, v2, v51, v54
	s_waitcnt lgkmcnt(12)
	v_fma_f32 v51, v3, v50, v87
	v_fma_f32 v50, v2, v50, v86
	v_fma_f32 v50, -v3, v54, v50
	v_fma_f32 v51, v2, v54, v51
	s_waitcnt lgkmcnt(11)
	v_fma_f32 v54, v3, v50, v81
	v_fma_f32 v50, v2, v50, v80
	v_fma_f32 v50, -v3, v51, v50
	v_fma_f32 v54, v2, v51, v54
	s_waitcnt lgkmcnt(10)
	v_fma_f32 v51, v3, v50, v75
	v_fma_f32 v50, v2, v50, v74
	v_fma_f32 v50, -v3, v54, v50
	v_fma_f32 v51, v2, v54, v51
	s_waitcnt lgkmcnt(9)
	v_fma_f32 v54, v3, v50, v69
	v_fma_f32 v50, v2, v50, v68
	v_fma_f32 v50, -v3, v51, v50
	v_fma_f32 v54, v2, v51, v54
	s_waitcnt lgkmcnt(8)
	v_fma_f32 v51, v3, v50, v65
	v_fma_f32 v50, v2, v50, v64
	v_fma_f32 v50, -v3, v54, v50
	v_fma_f32 v51, v2, v54, v51
	s_waitcnt lgkmcnt(7)
	v_fma_f32 v54, v3, v50, v61
	v_fma_f32 v50, v2, v50, v60
	v_fma_f32 v50, -v3, v51, v50
	v_fma_f32 v54, v2, v51, v54
	s_waitcnt lgkmcnt(6)
	v_fma_f32 v51, v3, v50, v57
	v_fma_f32 v50, v2, v50, v56
	v_fma_f32 v50, -v3, v54, v50
	v_fma_f32 v51, v2, v54, v51
	s_waitcnt lgkmcnt(5)
	v_fma_f32 v54, v3, v50, v53
	v_fma_f32 v50, v2, v50, v52
	v_fma_f32 v50, -v3, v51, v50
	v_fma_f32 v53, v2, v51, v54
	s_waitcnt lgkmcnt(4)
	v_fma_f32 v51, v3, v50, v49
	v_fma_f32 v48, v2, v50, v48
	v_fma_f32 v48, -v3, v53, v48
	v_fma_f32 v49, v2, v53, v51
	s_waitcnt lgkmcnt(3)
	v_fma_f32 v50, v3, v48, v47
	v_fma_f32 v46, v2, v48, v46
	v_fma_f32 v46, -v3, v49, v46
	v_fma_f32 v47, v2, v49, v50
	s_waitcnt lgkmcnt(2)
	v_fma_f32 v48, v3, v46, v45
	v_fma_f32 v44, v2, v46, v44
	v_fma_f32 v44, -v3, v47, v44
	v_fma_f32 v45, v2, v47, v48
	s_waitcnt lgkmcnt(0)
	v_mfma_f32_16x16x32_bf16 v[32:35], v[36:39], v[32:35], 0
	v_fma_f32 v46, v3, v44, v43
	v_fma_f32 v42, v2, v44, v42
	v_fma_f32 v42, -v3, v45, v42
	v_fma_f32 v43, v2, v45, v46
	v_mfma_f32_16x16x32_bf16 v[28:31], v[36:39], v[28:31], 0
	v_mfma_f32_16x16x32_bf16 v[20:23], v[36:39], v[20:23], 0
	s_nop 1
	ds_write2_b32 v0, v32, v28 offset1:16
	ds_write2_b32 v0, v33, v29 offset0:132 offset1:148
	ds_write2_b32 v137, v34, v30 offset0:8 offset1:24
	v_mfma_f32_16x16x32_bf16 v[12:15], v[36:39], v[12:15], 0
	ds_write2_b32 v137, v35, v31 offset0:140 offset1:156
	s_nop 6
	ds_write2_b32 v0, v20, v12 offset0:32 offset1:48
	ds_write2_b32 v0, v21, v13 offset0:164 offset1:180
	v_mfma_f32_16x16x32_bf16 v[24:27], v[36:39], v[24:27], 0
	v_fma_f32 v44, v3, v42, v41
	v_fma_f32 v40, v2, v42, v40
	v_fma_f32 v40, -v3, v43, v40
	v_fma_f32 v41, v2, v43, v44
	s_lshl_b32 s11, s10, 1
	s_mul_i32 s1, s10, 0x88
	v_mfma_f32_16x16x32_bf16 v[16:19], v[36:39], v[16:19], 0
	ds_write2_b32 v137, v22, v14 offset0:40 offset1:56
	ds_write2_b32 v137, v23, v15 offset0:172 offset1:188
	s_nop 5
	ds_write2_b32 v0, v24, v16 offset0:64 offset1:80
	ds_write2_b32 v0, v25, v17 offset0:196 offset1:212
	ds_write2_b32 v137, v26, v18 offset0:72 offset1:88
	ds_write2_b32 v137, v27, v19 offset0:204 offset1:220
	v_mfma_f32_16x16x32_bf16 v[8:11], v[36:39], v[8:11], 0
	s_ashr_i32 s10, s9, 31
	s_mul_hi_i32 s5, s11, 0x44
	s_add_u32 s4, s1, s9
	v_mfma_f32_16x16x32_bf16 v[4:7], v[36:39], v[4:7], 0
	s_nop 7
	ds_write2_b32 v0, v8, v4 offset0:96 offset1:112
	ds_write2_b32 v0, v9, v5 offset0:228 offset1:244
	ds_write2_b32 v137, v10, v6 offset0:104 offset1:120
	ds_write2_b32 v137, v11, v7 offset0:236 offset1:252
	s_waitcnt lgkmcnt(0)
	v_mul_f32_e32 v0, v3, v41
	ds_read2st64_b32 v[4:5], v138 offset0:12 offset1:13
	ds_read2st64_b32 v[6:7], v139 offset0:14 offset1:15
	ds_read2st64_b32 v[8:9], v140 offset0:16 offset1:17
	ds_read2st64_b32 v[10:11], v141 offset0:18 offset1:19
	ds_read2st64_b32 v[12:13], v146 offset0:20 offset1:21
	ds_read2st64_b32 v[14:15], v147 offset0:22 offset1:23
	ds_read2st64_b32 v[16:17], v148 offset0:24 offset1:25
	ds_read2st64_b32 v[18:19], v149 offset0:26 offset1:27
	ds_read2st64_b32 v[20:21], v150 offset0:28 offset1:29
	ds_read2st64_b32 v[22:23], v151 offset0:30 offset1:31
	ds_read2st64_b32 v[24:25], v152 offset0:32 offset1:33
	ds_read2st64_b32 v[26:27], v153 offset0:34 offset1:35
	ds_read2st64_b32 v[28:29], v154 offset0:36 offset1:37
	ds_read2st64_b32 v[30:31], v155 offset0:38 offset1:39
	ds_read2st64_b32 v[32:33], v156 offset0:40 offset1:41
	ds_read2st64_b32 v[34:35], v157 offset0:42 offset1:43
	v_fma_f32 v0, v2, v40, -v0
	s_waitcnt lgkmcnt(14)
	v_add_f32_e32 v0, v0, v4
	v_mul_f32_e32 v4, v3, v40
	v_fmac_f32_e32 v4, v2, v41
	v_add_f32_e32 v4, v4, v5
	v_mul_f32_e32 v5, v3, v4
	v_mul_f32_e32 v4, v2, v4
	v_fmac_f32_e32 v4, v3, v0
	v_fma_f32 v5, v2, v0, -v5
	v_add_f32_e32 v0, v7, v4
	v_add_f32_e32 v5, v6, v5
	s_waitcnt lgkmcnt(13)
	v_fma_f32 v4, -v0, v3, v8
	v_fma_f32 v0, v0, v2, v9
	v_fma_f32 v0, v5, v3, v0
	v_fma_f32 v4, v5, v2, v4
	s_waitcnt lgkmcnt(12)
	v_fma_f32 v5, -v0, v3, v10
	v_fma_f32 v0, v0, v2, v11
	v_fma_f32 v0, v4, v3, v0
	v_fma_f32 v5, v4, v2, v5
	s_waitcnt lgkmcnt(11)
	v_fma_f32 v4, -v0, v3, v12
	v_fma_f32 v0, v0, v2, v13
	v_fma_f32 v0, v5, v3, v0
	v_fma_f32 v4, v5, v2, v4
	s_waitcnt lgkmcnt(10)
	v_fma_f32 v5, -v0, v3, v14
	v_fma_f32 v0, v0, v2, v15
	v_fma_f32 v0, v4, v3, v0
	v_fma_f32 v5, v4, v2, v5
	s_waitcnt lgkmcnt(9)
	v_fma_f32 v4, -v0, v3, v16
	v_fma_f32 v0, v0, v2, v17
	v_fma_f32 v0, v5, v3, v0
	v_fma_f32 v4, v5, v2, v4
	s_waitcnt lgkmcnt(8)
	v_fma_f32 v5, -v0, v3, v18
	v_fma_f32 v0, v0, v2, v19
	v_fma_f32 v0, v4, v3, v0
	v_fma_f32 v5, v4, v2, v5
	s_waitcnt lgkmcnt(7)
	v_fma_f32 v4, -v0, v3, v20
	v_fma_f32 v0, v0, v2, v21
	v_fma_f32 v0, v5, v3, v0
	v_fma_f32 v4, v5, v2, v4
	s_waitcnt lgkmcnt(6)
	v_fma_f32 v5, -v0, v3, v22
	v_fma_f32 v0, v0, v2, v23
	v_fma_f32 v0, v4, v3, v0
	v_fma_f32 v5, v4, v2, v5
	s_waitcnt lgkmcnt(5)
	v_fma_f32 v4, -v0, v3, v24
	v_fma_f32 v0, v0, v2, v25
	v_fma_f32 v0, v5, v3, v0
	v_fma_f32 v4, v5, v2, v4
	s_waitcnt lgkmcnt(4)
	v_fma_f32 v5, -v0, v3, v26
	v_fma_f32 v0, v0, v2, v27
	v_fma_f32 v0, v4, v3, v0
	v_fma_f32 v5, v4, v2, v5
	s_waitcnt lgkmcnt(3)
	v_fma_f32 v4, -v0, v3, v28
	v_fma_f32 v0, v0, v2, v29
	v_fma_f32 v0, v5, v3, v0
	v_fma_f32 v4, v5, v2, v4
	s_waitcnt lgkmcnt(2)
	v_fma_f32 v5, -v0, v3, v30
	v_fma_f32 v0, v0, v2, v31
	v_fma_f32 v0, v4, v3, v0
	v_fma_f32 v5, v4, v2, v5
	s_waitcnt lgkmcnt(1)
	v_fma_f32 v4, v3, v5, v33
	v_fma_f32 v6, v2, v5, v32
	v_fma_f32 v6, -v3, v0, v6
	v_fma_f32 v0, v2, v0, v4
	v_mul_f32_e32 v4, v3, v0
	v_mul_f32_e32 v3, v3, v6
	v_fmac_f32_e32 v3, v2, v0
	s_waitcnt lgkmcnt(0)
	v_mov_b32_e32 v0, s59
	v_fma_f32 v4, v2, v6, -v4
	s_waitcnt lgkmcnt(0)
	v_add_f32_e32 v5, v35, v3
	ds_read_b64 v[2:3], v0
	s_addc_u32 s5, s5, s10
	s_ashr_i32 s1, s0, 31
	s_lshl_b64 s[22:23], s[4:5], 10
	s_lshl_b64 s[4:5], s[0:1], 6
	s_add_u32 s1, s22, s4
	s_addc_u32 s17, s23, s5
	v_or_b32_e32 v6, s1, v136
	v_mov_b32_e32 v7, s17
	s_waitcnt lgkmcnt(0)
	v_readfirstlane_b32 s1, v3
	v_readfirstlane_b32 s17, v2
	v_add_f32_e32 v4, v34, v4
	v_mov_b32_e32 v3, s1
	v_mov_b32_e32 v2, s17
	v_lshl_add_u64 v[2:3], v[6:7], 3, v[2:3]
	s_mov_b32 s1, 0xc00000
	v_add_co_u32_e32 v2, vcc, s1, v2
	v_mov_b32_e32 v42, v204
	s_nop 0
	v_addc_co_u32_e32 v3, vcc, 0, v3, vcc
	global_store_dwordx2 v[2:3], v[4:5], off
	ds_read_b64 v[2:3], v0
	v_readfirstlane_b32 s1, v42
	s_lshr_b32 s1, s1, 6
	s_mulk_i32 s1, 0x3e00
	s_add_i32 s17, s1, 0
	v_readlane_b32 s1, v244, 25
	v_and_b32_e32 v136, 63, v42
	s_add_i32 s0, s0, s1
	s_waitcnt lgkmcnt(0)
	v_readfirstlane_b32 s22, v2
	v_lshl_or_b32 v2, s0, 6, v136
	v_readfirstlane_b32 s23, v3
	v_ashrrev_i32_e32 v3, 31, v2
	s_mov_b32 s1, 0x200000
	v_lshl_add_u64 v[2:3], v[2:3], 4, s[22:23]
	v_add_co_u32_e32 v2, vcc, s1, v2
	s_ashr_i32 s1, s0, 31
	s_lshl_b64 s[0:1], s[0:1], 13
	s_add_u32 s0, s22, s0
	v_and_b32_e32 v37, 15, v42
	s_addc_u32 s1, s23, s1
	v_and_b32_e32 v0, 48, v42
	v_lshl_add_u64 v[4:5], s[0:1], 0, v[0:1]
	v_lshlrev_b32_e32 v6, 6, v37
	v_mov_b32_e32 v7, v1
	v_lshl_add_u64 v[6:7], v[4:5], 0, v[6:7]
	s_mov_b64 s[0:1], 0x240000
	v_addc_co_u32_e32 v3, vcc, 0, v3, vcc
	v_lshl_add_u64 v[8:9], v[6:7], 0, s[0:1]
	s_mov_b32 s0, 0x240000
	v_add_co_u32_e32 v10, vcc, s0, v6
	global_load_dwordx2 v[2:3], v[2:3], off
	s_nop 0
	global_load_dwordx4 v[28:31], v[8:9], off offset:1024
	global_load_dwordx4 v[24:27], v[8:9], off offset:2048
	global_load_dwordx4 v[16:19], v[8:9], off offset:3072
	v_addc_co_u32_e32 v11, vcc, 0, v7, vcc
	s_waitcnt lgkmcnt(0)
	v_add_co_u32_e32 v4, vcc, 0x241000, v6
	v_mul_u32_u24_e32 v38, 48, v37
	s_nop 0
	v_addc_co_u32_e32 v5, vcc, 0, v7, vcc
	global_load_dwordx4 v[32:35], v[10:11], off
	global_load_dwordx4 v[20:23], v[4:5], off
	global_load_dwordx4 v[12:15], v[4:5], off offset:1024
	s_nop 0
	global_load_dwordx4 v[8:11], v[4:5], off offset:2048
	s_nop 0
	global_load_dwordx4 v[4:7], v[4:5], off offset:3072
	v_cmp_gt_u32_e32 vcc, 32, v136
	v_mov_b32_e32 v36, 0
	v_add3_u32 v159, s17, v38, v0
	v_mov_b32_e32 v38, 0
	v_mov_b32_e32 v39, 0
	v_mov_b32_e32 v40, 0
	v_mov_b32_e32 v41, 0
	s_and_saveexec_b64 s[0:1], vcc
	ds_read_b128 v[38:41], v159 offset:2304
	s_or_b64 exec, exec, s[0:1]
	s_waitcnt vmcnt(0) lgkmcnt(0)
	v_mfma_f32_16x16x32_bf16 v[44:47], v[38:41], v[32:35], 0
	v_bfe_u32 v43, v42, 4, 2
	v_lshlrev_b32_e32 v37, 2, v37
	v_mul_u32_u24_e32 v43, 0x840, v43
	v_mfma_f32_16x16x32_bf16 v[48:51], v[38:41], v[28:31], 0
	v_add3_u32 v37, s17, v37, v43
	v_add_u32_e32 v137, 0xc00, v37
	v_add_u32_e32 v138, 0x1000, v37
	v_mfma_f32_16x16x32_bf16 v[52:55], v[38:41], v[24:27], 0
	v_lshl_add_u32 v139, v136, 2, s17
	s_nop 2
	ds_write2_b32 v137, v44, v48 offset1:16
	ds_write2_b32 v137, v45, v49 offset0:132 offset1:148
	v_mfma_f32_16x16x32_bf16 v[56:59], v[38:41], v[16:19], 0
	ds_write2_b32 v138, v46, v50 offset0:8 offset1:24
	ds_write2_b32 v138, v47, v51 offset0:140 offset1:156
	s_nop 5
	ds_write2_b32 v137, v52, v56 offset0:32 offset1:48
	ds_write2_b32 v137, v53, v57 offset0:164 offset1:180
	v_mfma_f32_16x16x32_bf16 v[60:63], v[38:41], v[20:23], 0
	v_add_u32_e32 v140, 0xf0, v139
	v_add_u32_e32 v141, 0xe0, v139
	v_add_u32_e32 v146, 0xd0, v139
	v_mfma_f32_16x16x32_bf16 v[44:47], v[38:41], v[12:15], 0
	ds_write2_b32 v138, v54, v58 offset0:40 offset1:56
	ds_write2_b32 v138, v55, v59 offset0:172 offset1:188
	s_nop 5
	ds_write2_b32 v137, v60, v44 offset0:64 offset1:80
	ds_write2_b32 v137, v61, v45 offset0:196 offset1:212
	ds_write2_b32 v138, v62, v46 offset0:72 offset1:88
	ds_write2_b32 v138, v63, v47 offset0:204 offset1:220
	v_mfma_f32_16x16x32_bf16 v[48:51], v[38:41], v[8:11], 0
	v_add_u32_e32 v147, 0xc0, v139
	v_add_u32_e32 v148, 0xb0, v139
	v_add_u32_e32 v149, 0xa0, v139
	v_mfma_f32_16x16x32_bf16 v[38:41], v[38:41], v[4:7], 0
	s_nop 7
	ds_write2_b32 v137, v48, v38 offset0:96 offset1:112
	ds_write2_b32 v137, v49, v39 offset0:228 offset1:244
	ds_write2_b32 v138, v50, v40 offset0:104 offset1:120
	ds_write2_b32 v138, v51, v41 offset0:236 offset1:252
	s_waitcnt lgkmcnt(0)
	v_add_u32_e32 v150, 0x90, v139
	v_add_u32_e32 v151, 0x80, v139
	v_add_u32_e32 v152, 0x70, v139
	v_add_u32_e32 v153, 0x60, v139
	v_add_u32_e32 v154, 0x50, v139
	v_add_u32_e32 v155, 64, v139
	v_add_u32_e32 v156, 48, v139
	v_add_u32_e32 v157, 32, v139
	v_add_u32_e32 v158, 16, v139
	ds_read2st64_b32 v[134:135], v140 offset0:42 offset1:43
	ds_read2st64_b32 v[132:133], v141 offset0:40 offset1:41
	ds_read2st64_b32 v[130:131], v146 offset0:38 offset1:39
	ds_read2st64_b32 v[126:127], v147 offset0:36 offset1:37
	ds_read2st64_b32 v[122:123], v148 offset0:34 offset1:35
	ds_read2st64_b32 v[118:119], v149 offset0:32 offset1:33
	ds_read2st64_b32 v[116:117], v150 offset0:30 offset1:31
	ds_read2st64_b32 v[112:113], v151 offset0:28 offset1:29
	ds_read2st64_b32 v[108:109], v152 offset0:26 offset1:27
	ds_read2st64_b32 v[102:103], v153 offset0:24 offset1:25
	ds_read2st64_b32 v[96:97], v154 offset0:22 offset1:23
	ds_read2st64_b32 v[90:91], v155 offset0:20 offset1:21
	ds_read2st64_b32 v[86:87], v156 offset0:18 offset1:19
	ds_read2st64_b32 v[82:83], v157 offset0:16 offset1:17
	ds_read2st64_b32 v[76:77], v158 offset0:14 offset1:15
	ds_read2st64_b32 v[70:71], v139 offset0:12 offset1:13
	s_waitcnt lgkmcnt(0)
	v_mov_b32_e32 v37, 0
	v_mov_b32_e32 v38, 0
	v_mov_b32_e32 v39, 0
	s_and_saveexec_b64 s[0:1], vcc
	v_or_b32_e32 v36, 0xfffff0, v42
	v_mul_i32_i24_e32 v36, 48, v36
	v_add3_u32 v0, s17, v36, v0
	ds_read_b128 v[36:39], v0 offset:2304
	s_or_b64 exec, exec, s[0:1]
	s_waitcnt lgkmcnt(0)
	v_mfma_f32_16x16x32_bf16 v[40:43], v[36:39], v[32:35], 0
	v_mfma_f32_16x16x32_bf16 v[44:47], v[36:39], v[28:31], 0
	s_nop 7
	ds_write2_b32 v137, v40, v44 offset1:16
	ds_write2_b32 v137, v41, v45 offset0:132 offset1:148
	ds_write2_b32 v138, v42, v46 offset0:8 offset1:24
	v_mfma_f32_16x16x32_bf16 v[48:51], v[36:39], v[24:27], 0
	v_mfma_f32_16x16x32_bf16 v[52:55], v[36:39], v[16:19], 0
	ds_write2_b32 v138, v43, v47 offset0:140 offset1:156
	s_nop 6
	ds_write2_b32 v137, v48, v52 offset0:32 offset1:48
	ds_write2_b32 v137, v49, v53 offset0:164 offset1:180
	v_mfma_f32_16x16x32_bf16 v[56:59], v[36:39], v[20:23], 0
	v_mfma_f32_16x16x32_bf16 v[40:43], v[36:39], v[12:15], 0
	ds_write2_b32 v138, v50, v54 offset0:40 offset1:56
	ds_write2_b32 v138, v51, v55 offset0:172 offset1:188
	s_nop 5
	ds_write2_b32 v137, v56, v40 offset0:64 offset1:80
	ds_write2_b32 v137, v57, v41 offset0:196 offset1:212
	ds_write2_b32 v138, v58, v42 offset0:72 offset1:88
	ds_write2_b32 v138, v59, v43 offset0:204 offset1:220
	v_mfma_f32_16x16x32_bf16 v[44:47], v[36:39], v[8:11], 0
	v_mov_b32_e32 v40, 0
	v_mov_b32_e32 v41, 0
	v_mfma_f32_16x16x32_bf16 v[36:39], v[36:39], v[4:7], 0
	s_nop 7
	ds_write2_b32 v137, v44, v36 offset0:96 offset1:112
	ds_write2_b32 v137, v45, v37 offset0:228 offset1:244
	ds_write2_b32 v138, v46, v38 offset0:104 offset1:120
	ds_write2_b32 v138, v47, v39 offset0:236 offset1:252
	s_waitcnt lgkmcnt(0)
	ds_read2st64_b32 v[128:129], v140 offset0:42 offset1:43
	ds_read2st64_b32 v[124:125], v141 offset0:40 offset1:41
	ds_read2st64_b32 v[120:121], v146 offset0:38 offset1:39
	ds_read2st64_b32 v[114:115], v147 offset0:36 offset1:37
	ds_read2st64_b32 v[110:111], v148 offset0:34 offset1:35
	ds_read2st64_b32 v[104:105], v149 offset0:32 offset1:33
	ds_read2st64_b32 v[98:99], v150 offset0:30 offset1:31
	ds_read2st64_b32 v[92:93], v151 offset0:28 offset1:29
	ds_read2st64_b32 v[84:85], v152 offset0:26 offset1:27
	ds_read2st64_b32 v[78:79], v153 offset0:24 offset1:25
	ds_read2st64_b32 v[72:73], v154 offset0:22 offset1:23
	ds_read2st64_b32 v[66:67], v155 offset0:20 offset1:21
	ds_read2st64_b32 v[62:63], v156 offset0:18 offset1:19
	ds_read2st64_b32 v[58:59], v157 offset0:16 offset1:17
	ds_read2st64_b32 v[54:55], v158 offset0:14 offset1:15
	ds_read2st64_b32 v[50:51], v139 offset0:12 offset1:13
	s_waitcnt lgkmcnt(0)
	v_mov_b32_e32 v36, 0
	v_mov_b32_e32 v38, 0
	v_mov_b32_e32 v39, 0
	s_and_saveexec_b64 s[0:1], vcc
	ds_read_b128 v[38:41], v159 offset:768
	s_or_b64 exec, exec, s[0:1]
	s_waitcnt lgkmcnt(0)
	v_mfma_f32_16x16x32_bf16 v[42:45], v[38:41], v[32:35], 0
	v_mov_b32_e32 v37, 0
	v_mfma_f32_16x16x32_bf16 v[46:49], v[38:41], v[28:31], 0
	s_nop 7
	ds_write2_b32 v137, v42, v46 offset1:16
	ds_write2_b32 v137, v43, v47 offset0:132 offset1:148
	ds_write2_b32 v138, v44, v48 offset0:8 offset1:24
	v_mfma_f32_16x16x32_bf16 v[160:163], v[38:41], v[24:27], 0
	v_mfma_f32_16x16x32_bf16 v[164:167], v[38:41], v[16:19], 0
	ds_write2_b32 v138, v45, v49 offset0:140 offset1:156
	s_nop 6
	ds_write2_b32 v137, v160, v164 offset0:32 offset1:48
	ds_write2_b32 v137, v161, v165 offset0:164 offset1:180
	v_mfma_f32_16x16x32_bf16 v[168:171], v[38:41], v[20:23], 0
	v_mfma_f32_16x16x32_bf16 v[42:45], v[38:41], v[12:15], 0
	ds_write2_b32 v138, v162, v166 offset0:40 offset1:56
	ds_write2_b32 v138, v163, v167 offset0:172 offset1:188
	s_nop 5
	ds_write2_b32 v137, v168, v42 offset0:64 offset1:80
	ds_write2_b32 v137, v169, v43 offset0:196 offset1:212
	ds_write2_b32 v138, v170, v44 offset0:72 offset1:88
	ds_write2_b32 v138, v171, v45 offset0:204 offset1:220
	v_mfma_f32_16x16x32_bf16 v[46:49], v[38:41], v[8:11], 0
	v_mfma_f32_16x16x32_bf16 v[38:41], v[38:41], v[4:7], 0
	s_nop 7
	ds_write2_b32 v137, v46, v38 offset0:96 offset1:112
	ds_write2_b32 v137, v47, v39 offset0:228 offset1:244
	ds_write2_b32 v138, v48, v40 offset0:104 offset1:120
	ds_write2_b32 v138, v49, v41 offset0:236 offset1:252
	s_waitcnt lgkmcnt(0)
	ds_read2st64_b32 v[106:107], v140 offset0:42 offset1:43
	ds_read2st64_b32 v[100:101], v141 offset0:40 offset1:41
	ds_read2st64_b32 v[94:95], v146 offset0:38 offset1:39
	ds_read2st64_b32 v[88:89], v147 offset0:36 offset1:37
	ds_read2st64_b32 v[80:81], v148 offset0:34 offset1:35
	ds_read2st64_b32 v[74:75], v149 offset0:32 offset1:33
	ds_read2st64_b32 v[68:69], v150 offset0:30 offset1:31
	ds_read2st64_b32 v[64:65], v151 offset0:28 offset1:29
	ds_read2st64_b32 v[60:61], v152 offset0:26 offset1:27
	ds_read2st64_b32 v[56:57], v153 offset0:24 offset1:25
	ds_read2st64_b32 v[52:53], v154 offset0:22 offset1:23
	ds_read2st64_b32 v[48:49], v155 offset0:20 offset1:21
	ds_read2st64_b32 v[46:47], v156 offset0:18 offset1:19
	ds_read2st64_b32 v[44:45], v157 offset0:16 offset1:17
	ds_read2st64_b32 v[42:43], v158 offset0:14 offset1:15
	ds_read2st64_b32 v[40:41], v139 offset0:12 offset1:13
	s_waitcnt lgkmcnt(0)
	v_mov_b32_e32 v38, 0
	v_mov_b32_e32 v39, 0
	s_and_saveexec_b64 s[0:1], vcc
	s_cbranch_execz .LBB0_594
	ds_read_b128 v[36:39], v159
	s_branch .LBB0_594
